# LayerNorm job: rows of the wave's other three tokens fetched up front into free VGPRs (cross-token prefetch), on top of late MLA DMA issue
# baseline (speedup 1.0000x reference)
.LBB0_936:
	v_mov_b32_e32 v0, v178
	v_readlane_b32 s0, v228, 16
	v_ashrrev_i32_e32 v1, 4, v0
	v_and_b32_e32 v1, -4, v1
	s_add_i32 s0, s0, s8
	v_add_u32_e32 v22, s0, v1
	v_lshlrev_b32_e32 v0, 2, v0
	v_add_u32_e32 v10, -3, v22
	v_and_b32_e32 v21, 0xfc, v0
	v_and_b32_e32 v0, 64, v192
	v_ashrrev_i32_e32 v11, 31, v10
	v_add_u32_e32 v20, s8, v1
	v_add_u32_e32 v2, 64, v0
	v_lshlrev_b64 v[0:1], 12, v[10:11]
	v_lshl_add_u64 v[0:1], s[58:59], 0, v[0:1]
	v_lshlrev_b32_e32 v96, 2, v21
	v_lshl_add_u64 v[30:31], v[0:1], 0, v[96:97]
	v_xor_b32_e32 v0, 32, v192
	v_cmp_lt_i32_e32 vcc, v0, v2
	v_ashrrev_i32_e32 v9, 12, v10
	v_add_u32_e32 v8, -3, v20
	v_cndmask_b32_e32 v0, v192, v0, vcc
	v_lshlrev_b32_e32 v46, 2, v0
	v_xor_b32_e32 v0, 16, v192
	v_cmp_lt_i32_e32 vcc, v0, v2
	v_add_u32_e32 v9, s38, v9
	v_mul_hi_i32_i24_e32 v11, 0x3000, v9
	v_cndmask_b32_e32 v0, v192, v0, vcc
	v_lshlrev_b32_e32 v47, 2, v0
	v_xor_b32_e32 v0, 8, v192
	v_cmp_lt_i32_e32 vcc, v0, v2
	v_mul_i32_i24_e32 v10, 0x3000, v9
	v_ashrrev_i32_e32 v9, 31, v8
	v_cndmask_b32_e32 v0, v192, v0, vcc
	v_lshlrev_b32_e32 v49, 2, v0
	v_xor_b32_e32 v0, 4, v192
	v_cmp_lt_i32_e32 vcc, v0, v2
	v_lshlrev_b64 v[8:9], 11, v[8:9]
	v_lshl_add_u64 v[34:35], s[16:17], 0, v[10:11]
	v_cndmask_b32_e32 v0, v192, v0, vcc
	v_lshlrev_b32_e32 v50, 2, v0
	v_xor_b32_e32 v0, 2, v192
	v_cmp_lt_i32_e32 vcc, v0, v2
	v_lshl_add_u64 v[32:33], s[80:81], 0, v[8:9]
	s_mov_b64 s[0:1], 0x1000
	v_cndmask_b32_e32 v0, v192, v0, vcc
	v_lshlrev_b32_e32 v51, 2, v0
	v_xor_b32_e32 v0, 1, v192
	v_cmp_lt_i32_e32 vcc, v0, v2
	v_lshl_add_u64 v[36:37], v[34:35], 0, s[0:1]
	s_mov_b32 s0, 0x800000
	v_cndmask_b32_e32 v0, v192, v0, vcc
	v_lshlrev_b32_e32 v48, 2, v0
	global_load_dwordx4 v[232:235], v96, s[4:5] offset:1024
	global_load_dwordx4 v[236:239], v96, s[4:5] offset:2048
	global_load_dwordx4 v[240:243], v96, s[4:5] offset:3072
	global_load_dwordx4 v[244:247], v96, s[6:7] offset:1024
	global_load_dwordx4 v[248:251], v96, s[6:7] offset:2048
	global_load_dwordx4 v[252:255], v96, s[6:7] offset:3072
	global_load_dwordx4 v[0:3], v[30:31], off offset:3072
	global_load_dwordx4 v[4:7], v[30:31], off offset:2048
	global_load_dwordx4 v[16:19], v[30:31], off offset:1024
	v_readlane_b32 s10, v227, 19
	v_readlane_b32 s11, v227, 20
	s_waitcnt vmcnt(2)
	v_mov_b32_e32 v13, v0
	s_waitcnt vmcnt(1)
	v_mov_b32_e32 v12, v4
	v_mov_b32_e32 v14, v5
	v_mov_b32_e32 v15, v1
	v_pk_add_f32 v[12:13], v[12:13], v[14:15]
	v_mov_b32_e32 v14, v6
	v_mov_b32_e32 v15, v2
	v_pk_add_f32 v[12:13], v[12:13], v[14:15]
	v_mov_b32_e32 v14, v7
	v_mov_b32_e32 v15, v3
	v_pk_add_f32 v[28:29], v[12:13], v[14:15]
	global_load_dwordx4 v[24:27], v[30:31], off
	global_load_dwordx4 v[8:11], v96, s[4:5]
	global_load_dwordx4 v[12:15], v96, s[6:7]
	s_mov_b64 s[100:101], 0x1000
	v_lshl_add_u64 v[162:163], v[30:31], 0, s[100:101]
	s_mov_b64 s[100:101], 0x2000
	v_lshl_add_u64 v[164:165], v[30:31], 0, s[100:101]
	s_mov_b64 s[100:101], 0x3000
	v_lshl_add_u64 v[166:167], v[30:31], 0, s[100:101]
	global_load_dwordx4 v[110:113], v[162:163], off offset:3072
	global_load_dwordx4 v[106:109], v[162:163], off offset:2048
	global_load_dwordx4 v[102:105], v[162:163], off offset:1024
	global_load_dwordx4 v[98:101], v[162:163], off
	global_load_dwordx4 v[126:129], v[164:165], off offset:3072
	global_load_dwordx4 v[122:125], v[164:165], off offset:2048
	global_load_dwordx4 v[118:121], v[164:165], off offset:1024
	global_load_dwordx4 v[114:117], v[164:165], off
	global_load_dwordx4 v[142:145], v[166:167], off offset:3072
	global_load_dwordx4 v[138:141], v[166:167], off offset:2048
	global_load_dwordx4 v[134:137], v[166:167], off offset:1024
	global_load_dwordx4 v[130:133], v[166:167], off
	s_waitcnt vmcnt(15)
	v_mov_b32_e32 v39, v16
	v_mov_b32_e32 v41, v17
	s_waitcnt vmcnt(14)
	v_mov_b32_e32 v38, v24
	v_mov_b32_e32 v40, v25
	v_pk_add_f32 v[38:39], v[38:39], v[40:41]
	v_mov_b32_e32 v40, v26
	v_mov_b32_e32 v41, v18
	v_pk_add_f32 v[38:39], v[38:39], v[40:41]
	v_mov_b32_e32 v40, v27
	v_mov_b32_e32 v41, v19
	v_pk_add_f32 v[38:39], v[38:39], v[40:41]
	s_nop 0
	v_add_f32_e32 v23, 0, v38
	v_add_f32_e32 v23, v23, v39
	v_add_f32_e32 v23, v23, v28
	v_add_f32_e32 v23, v23, v29
	ds_bpermute_b32 v28, v46, v23
	s_waitcnt lgkmcnt(0)
	v_add_f32_e32 v23, v23, v28
	ds_bpermute_b32 v28, v47, v23
	s_waitcnt lgkmcnt(0)
	v_add_f32_e32 v23, v23, v28
	ds_bpermute_b32 v28, v49, v23
	s_waitcnt lgkmcnt(0)
	v_add_f32_e32 v23, v23, v28
	ds_bpermute_b32 v28, v50, v23
	s_waitcnt lgkmcnt(0)
	v_add_f32_e32 v23, v23, v28
	ds_bpermute_b32 v28, v51, v23
	s_waitcnt lgkmcnt(0)
	v_add_f32_e32 v23, v23, v28
	ds_bpermute_b32 v28, v48, v23
	s_waitcnt lgkmcnt(0)
	v_add_f32_e32 v23, v23, v28
	v_mul_f32_e32 v42, 0x3a800000, v23
	v_pk_add_f32 v[24:25], v[24:25], v[42:43] op_sel_hi:[1,0] neg_lo:[0,1] neg_hi:[0,1]
	v_pk_add_f32 v[44:45], v[26:27], v[42:43] op_sel_hi:[1,0] neg_lo:[0,1] neg_hi:[0,1]
	v_pk_add_f32 v[26:27], v[16:17], v[42:43] op_sel_hi:[1,0] neg_lo:[0,1] neg_hi:[0,1]
	v_pk_add_f32 v[28:29], v[18:19], v[42:43] op_sel_hi:[1,0] neg_lo:[0,1] neg_hi:[0,1]
	v_mov_b32_e32 v18, v25
	v_mov_b32_e32 v19, v27
	v_pk_add_f32 v[38:39], v[4:5], v[42:43] op_sel_hi:[1,0] neg_lo:[0,1] neg_hi:[0,1]
	v_pk_add_f32 v[4:5], v[0:1], v[42:43] op_sel_hi:[1,0] neg_lo:[0,1] neg_hi:[0,1]
	v_mov_b32_e32 v16, v24
	v_mov_b32_e32 v17, v26
	v_pk_mul_f32 v[18:19], v[18:19], v[18:19]
	v_pk_add_f32 v[40:41], v[6:7], v[42:43] op_sel_hi:[1,0] neg_lo:[0,1] neg_hi:[0,1]
	v_pk_add_f32 v[6:7], v[2:3], v[42:43] op_sel_hi:[1,0] neg_lo:[0,1] neg_hi:[0,1]
	v_mov_b32_e32 v2, v5
	v_mov_b32_e32 v3, v39
	v_pk_fma_f32 v[16:17], v[16:17], v[16:17], v[18:19]
	v_mov_b32_e32 v18, v44
	v_mov_b32_e32 v19, v28
	v_mov_b32_e32 v0, v4
	v_mov_b32_e32 v1, v38
	v_pk_mul_f32 v[2:3], v[2:3], v[2:3]
	v_pk_fma_f32 v[16:17], v[18:19], v[18:19], v[16:17]
	v_mov_b32_e32 v18, v45
	v_mov_b32_e32 v19, v29
	v_pk_fma_f32 v[0:1], v[0:1], v[0:1], v[2:3]
	v_mov_b32_e32 v2, v6
	v_mov_b32_e32 v3, v40
	v_pk_fma_f32 v[16:17], v[18:19], v[18:19], v[16:17]
	v_pk_fma_f32 v[0:1], v[2:3], v[2:3], v[0:1]
	v_mov_b32_e32 v2, v7
	v_mov_b32_e32 v3, v41
	v_pk_fma_f32 v[0:1], v[2:3], v[2:3], v[0:1]
	v_add_f32_e32 v2, v16, v17
	v_add_f32_e32 v1, v1, v2
	v_add_f32_e32 v0, v0, v1
	ds_bpermute_b32 v1, v46, v0
	v_lshlrev_b32_e32 v16, 1, v21
	s_waitcnt lgkmcnt(0)
	v_add_f32_e32 v0, v0, v1
	ds_bpermute_b32 v1, v47, v0
	s_waitcnt lgkmcnt(0)
	v_add_f32_e32 v0, v0, v1
	ds_bpermute_b32 v1, v49, v0
	s_waitcnt lgkmcnt(0)
	v_add_f32_e32 v0, v0, v1
	ds_bpermute_b32 v1, v50, v0
	s_waitcnt lgkmcnt(0)
	v_add_f32_e32 v0, v0, v1
	ds_bpermute_b32 v1, v51, v0
	s_waitcnt lgkmcnt(0)
	v_add_f32_e32 v0, v0, v1
	ds_bpermute_b32 v1, v48, v0
	s_waitcnt lgkmcnt(0)
	v_add_f32_e32 v0, v0, v1
	v_fmamk_f32 v0, v0, 0x3a800000, v181
	v_cmp_gt_f32_e32 vcc, s0, v0
	v_mul_f32_e32 v1, 0x4b800000, v0
	s_nop 0
	v_cndmask_b32_e32 v0, v0, v1, vcc
	v_rsq_f32_e32 v0, v0
	s_nop 0
	v_mul_f32_e32 v1, 0x45800000, v0
	v_cndmask_b32_e32 v42, v0, v1, vcc
	v_pk_mul_f32 v[0:1], v[24:25], v[42:43] op_sel_hi:[1,0]
	v_pk_mul_f32 v[2:3], v[44:45], v[42:43] op_sel_hi:[1,0]
	s_waitcnt vmcnt(12)
	v_pk_fma_f32 v[0:1], v[8:9], v[0:1], v[12:13]
	v_cndmask_b32_e64 v8, 0, 1, s[10:11]
	v_pk_fma_f32 v[2:3], v[10:11], v[2:3], v[14:15]
	v_cmp_ne_u32_e64 s[0:1], 1, v8
	s_andn2_b64 vcc, exec, s[10:11]
	global_store_dwordx4 v[30:31], v[0:3], off
	s_cbranch_vccnz .LBB0_938
	v_lshl_add_u64 v[8:9], v[36:37], 0, v[96:97]
	global_load_dwordx4 v[8:11], v[8:9], off
	v_lshl_add_u64 v[12:13], v[34:35], 0, v[96:97]
	global_load_dwordx4 v[12:15], v[12:13], off
	v_mov_b32_e32 v17, v97
	s_waitcnt vmcnt(1)
	v_add_f32_e32 v8, 1.0, v8
	v_add_f32_e32 v9, 1.0, v9
	v_add_f32_e32 v10, 1.0, v10
	v_add_f32_e32 v11, 1.0, v11
	s_waitcnt vmcnt(0)
	v_fma_f32 v0, v0, v8, v12
	v_fma_f32 v1, v1, v9, v13
	v_fma_f32 v2, v2, v10, v14
	v_fmac_f32_e32 v15, v3, v11
	v_cvt_pk_bf16_f32 v0, v0, v1
	v_cvt_pk_bf16_f32 v1, v2, v15
	v_lshl_add_u64 v[2:3], v[32:33], 0, v[16:17]
	global_store_dwordx2 v[2:3], v[0:1], off

.LBB0_944:
	s_waitcnt vmcnt(12)
	v_add_u32_e32 v2, -2, v22
	v_ashrrev_i32_e32 v3, 31, v2
	v_lshlrev_b64 v[4:5], 12, v[2:3]
	v_lshl_add_u64 v[4:5], s[58:59], 0, v[4:5]
	v_lshl_add_u64 v[34:35], v[4:5], 0, v[96:97]
	v_mov_b32_e32 v8, v110
	v_mov_b32_e32 v9, v111
	v_mov_b32_e32 v10, v112
	v_mov_b32_e32 v11, v113
	v_mov_b32_e32 v12, v106
	v_mov_b32_e32 v13, v107
	v_mov_b32_e32 v14, v108
	v_mov_b32_e32 v15, v109
	v_ashrrev_i32_e32 v1, 12, v2
	v_add_u32_e32 v0, -2, v20
	v_add_u32_e32 v1, s38, v1
	v_mov_b32_e32 v40, v102
	v_mov_b32_e32 v41, v103
	v_mov_b32_e32 v42, v104
	v_mov_b32_e32 v43, v105
	v_mul_hi_i32_i24_e32 v3, 0x3000, v1
	v_mul_i32_i24_e32 v2, 0x3000, v1
	v_ashrrev_i32_e32 v1, 31, v0
	v_lshlrev_b64 v[0:1], 11, v[0:1]
	v_lshl_add_u64 v[36:37], s[16:17], 0, v[2:3]
	v_lshl_add_u64 v[32:33], s[80:81], 0, v[0:1]
	s_mov_b64 s[10:11], 0x1000
	v_lshl_add_u64 v[38:39], v[36:37], 0, s[10:11]
	s_mov_b32 s10, 0x800000
	v_mov_b32_e32 v5, v8
	v_mov_b32_e32 v4, v12
	v_mov_b32_e32 v6, v13
	v_mov_b32_e32 v7, v9
	v_pk_add_f32 v[4:5], v[4:5], v[6:7]
	v_mov_b32_e32 v6, v14
	v_mov_b32_e32 v7, v10
	v_pk_add_f32 v[4:5], v[4:5], v[6:7]
	v_mov_b32_e32 v6, v15
	v_mov_b32_e32 v7, v11
	v_pk_add_f32 v[44:45], v[4:5], v[6:7]
	v_mov_b32_e32 v52, v98
	v_mov_b32_e32 v53, v99
	v_mov_b32_e32 v54, v100
	v_mov_b32_e32 v55, v101
	global_load_dwordx4 v[0:3], v[24:25], off
	global_load_dwordx4 v[4:7], v[18:19], off
	v_mov_b32_e32 v57, v40
	v_mov_b32_e32 v59, v41
	v_mov_b32_e32 v56, v52
	v_mov_b32_e32 v58, v53
	v_pk_add_f32 v[56:57], v[56:57], v[58:59]
	v_mov_b32_e32 v58, v54
	v_mov_b32_e32 v59, v42
	v_pk_add_f32 v[56:57], v[56:57], v[58:59]
	v_mov_b32_e32 v58, v55
	v_mov_b32_e32 v59, v43
	v_pk_add_f32 v[56:57], v[56:57], v[58:59]
	s_nop 0
	v_add_f32_e32 v17, 0, v56
	v_add_f32_e32 v17, v17, v57
	v_add_f32_e32 v17, v17, v44
	v_add_f32_e32 v17, v17, v45
	ds_bpermute_b32 v21, v46, v17
	s_waitcnt lgkmcnt(0)
	v_add_f32_e32 v17, v17, v21
	ds_bpermute_b32 v21, v47, v17
	s_waitcnt lgkmcnt(0)
	v_add_f32_e32 v17, v17, v21
	ds_bpermute_b32 v21, v49, v17
	s_waitcnt lgkmcnt(0)
	v_add_f32_e32 v17, v17, v21
	ds_bpermute_b32 v21, v50, v17
	s_waitcnt lgkmcnt(0)
	v_add_f32_e32 v17, v17, v21
	ds_bpermute_b32 v21, v51, v17
	s_waitcnt lgkmcnt(0)
	v_add_f32_e32 v17, v17, v21
	ds_bpermute_b32 v21, v48, v17
	s_waitcnt lgkmcnt(0)
	v_add_f32_e32 v17, v17, v21
	v_mul_f32_e32 v44, 0x3a800000, v17
	v_pk_add_f32 v[52:53], v[52:53], v[44:45] op_sel_hi:[1,0] neg_lo:[0,1] neg_hi:[0,1]
	v_pk_add_f32 v[40:41], v[40:41], v[44:45] op_sel_hi:[1,0] neg_lo:[0,1] neg_hi:[0,1]
	v_mov_b32_e32 v58, v53
	v_mov_b32_e32 v59, v41
	v_pk_add_f32 v[54:55], v[54:55], v[44:45] op_sel_hi:[1,0] neg_lo:[0,1] neg_hi:[0,1]
	v_pk_add_f32 v[42:43], v[42:43], v[44:45] op_sel_hi:[1,0] neg_lo:[0,1] neg_hi:[0,1]
	v_mov_b32_e32 v56, v52
	v_mov_b32_e32 v57, v40
	v_pk_mul_f32 v[58:59], v[58:59], v[58:59]
	v_pk_add_f32 v[12:13], v[12:13], v[44:45] op_sel_hi:[1,0] neg_lo:[0,1] neg_hi:[0,1]
	v_pk_fma_f32 v[56:57], v[56:57], v[56:57], v[58:59]
	v_mov_b32_e32 v58, v54
	v_mov_b32_e32 v59, v42
	v_pk_fma_f32 v[56:57], v[58:59], v[58:59], v[56:57]
	v_mov_b32_e32 v58, v55
	v_mov_b32_e32 v59, v43
	v_pk_add_f32 v[8:9], v[8:9], v[44:45] op_sel_hi:[1,0] neg_lo:[0,1] neg_hi:[0,1]
	v_pk_fma_f32 v[56:57], v[58:59], v[58:59], v[56:57]
	v_mov_b32_e32 v58, v9
	v_mov_b32_e32 v59, v13
	v_pk_add_f32 v[14:15], v[14:15], v[44:45] op_sel_hi:[1,0] neg_lo:[0,1] neg_hi:[0,1]
	v_pk_add_f32 v[10:11], v[10:11], v[44:45] op_sel_hi:[1,0] neg_lo:[0,1] neg_hi:[0,1]
	v_mov_b32_e32 v44, v8
	v_mov_b32_e32 v45, v12
	v_pk_mul_f32 v[58:59], v[58:59], v[58:59]
	v_add_f32_e32 v17, v56, v57
	v_pk_fma_f32 v[44:45], v[44:45], v[44:45], v[58:59]
	v_mov_b32_e32 v58, v10
	v_mov_b32_e32 v59, v14
	v_pk_fma_f32 v[44:45], v[58:59], v[58:59], v[44:45]
	v_mov_b32_e32 v58, v11
	v_mov_b32_e32 v59, v15
	v_pk_fma_f32 v[44:45], v[58:59], v[58:59], v[44:45]
	s_nop 0
	v_add_f32_e32 v17, v45, v17
	v_add_f32_e32 v17, v44, v17
	ds_bpermute_b32 v21, v46, v17
	s_waitcnt lgkmcnt(0)
	v_add_f32_e32 v17, v17, v21
	ds_bpermute_b32 v21, v47, v17
	s_waitcnt lgkmcnt(0)
	v_add_f32_e32 v17, v17, v21
	ds_bpermute_b32 v21, v49, v17
	s_waitcnt lgkmcnt(0)
	v_add_f32_e32 v17, v17, v21
	ds_bpermute_b32 v21, v50, v17
	s_waitcnt lgkmcnt(0)
	v_add_f32_e32 v17, v17, v21
	ds_bpermute_b32 v21, v51, v17
	s_waitcnt lgkmcnt(0)
	v_add_f32_e32 v17, v17, v21
	ds_bpermute_b32 v21, v48, v17
	s_waitcnt lgkmcnt(0)
	v_add_f32_e32 v17, v17, v21
	v_fmamk_f32 v17, v17, 0x3a800000, v181
	v_cmp_gt_f32_e32 vcc, s10, v17
	v_mul_f32_e32 v21, 0x4b800000, v17
	s_nop 0
	v_cndmask_b32_e32 v17, v17, v21, vcc
	v_rsq_f32_e32 v17, v17
	s_nop 0
	v_mul_f32_e32 v21, 0x45800000, v17
	v_cndmask_b32_e32 v44, v17, v21, vcc
	v_pk_mul_f32 v[52:53], v[52:53], v[44:45] op_sel_hi:[1,0]
	s_and_b64 vcc, exec, s[0:1]
	s_waitcnt vmcnt(0)
	v_pk_fma_f32 v[0:1], v[0:1], v[52:53], v[4:5]
	v_pk_mul_f32 v[4:5], v[54:55], v[44:45] op_sel_hi:[1,0]
	s_nop 0
	v_pk_fma_f32 v[2:3], v[2:3], v[4:5], v[6:7]
	global_store_dwordx4 v[34:35], v[0:3], off
	s_cbranch_vccnz .LBB0_946
	v_lshl_add_u64 v[4:5], v[38:39], 0, v[96:97]
	global_load_dwordx4 v[4:7], v[4:5], off
	v_lshl_add_u64 v[52:53], v[36:37], 0, v[96:97]
	global_load_dwordx4 v[52:55], v[52:53], off
	v_mov_b32_e32 v17, v97
	s_waitcnt vmcnt(1)
	v_add_f32_e32 v4, 1.0, v4
	v_add_f32_e32 v5, 1.0, v5
	v_add_f32_e32 v6, 1.0, v6
	v_add_f32_e32 v7, 1.0, v7
	s_waitcnt vmcnt(0)
	v_fma_f32 v0, v0, v4, v52
	v_fma_f32 v1, v1, v5, v53
	v_fma_f32 v2, v2, v6, v54
	v_fmac_f32_e32 v55, v3, v7
	v_cvt_pk_bf16_f32 v0, v0, v1
	v_cvt_pk_bf16_f32 v1, v2, v55
	v_lshl_add_u64 v[2:3], v[32:33], 0, v[16:17]
	global_store_dwordx2 v[2:3], v[0:1], off

.LBB0_952:
	s_nop 0
	v_add_u32_e32 v2, -1, v22
	v_ashrrev_i32_e32 v3, 31, v2
	v_lshlrev_b64 v[4:5], 12, v[2:3]
	v_lshl_add_u64 v[4:5], s[58:59], 0, v[4:5]
	v_lshl_add_u64 v[34:35], v[4:5], 0, v[96:97]
	v_mov_b32_e32 v8, v126
	v_mov_b32_e32 v9, v127
	v_mov_b32_e32 v10, v128
	v_mov_b32_e32 v11, v129
	v_mov_b32_e32 v12, v122
	v_mov_b32_e32 v13, v123
	v_mov_b32_e32 v14, v124
	v_mov_b32_e32 v15, v125
	v_ashrrev_i32_e32 v1, 12, v2
	v_add_u32_e32 v0, -1, v20
	v_add_u32_e32 v1, s38, v1
	v_mov_b32_e32 v40, v118
	v_mov_b32_e32 v41, v119
	v_mov_b32_e32 v42, v120
	v_mov_b32_e32 v43, v121
	v_mul_hi_i32_i24_e32 v3, 0x3000, v1
	v_mul_i32_i24_e32 v2, 0x3000, v1
	v_ashrrev_i32_e32 v1, 31, v0
	v_lshlrev_b64 v[0:1], 11, v[0:1]
	v_lshl_add_u64 v[36:37], s[16:17], 0, v[2:3]
	v_lshl_add_u64 v[32:33], s[80:81], 0, v[0:1]
	s_mov_b64 s[10:11], 0x1000
	v_lshl_add_u64 v[38:39], v[36:37], 0, s[10:11]
	s_mov_b32 s10, 0x800000
	v_mov_b32_e32 v5, v8
	v_mov_b32_e32 v4, v12
	v_mov_b32_e32 v6, v13
	v_mov_b32_e32 v7, v9
	v_pk_add_f32 v[4:5], v[4:5], v[6:7]
	v_mov_b32_e32 v6, v14
	v_mov_b32_e32 v7, v10
	v_pk_add_f32 v[4:5], v[4:5], v[6:7]
	v_mov_b32_e32 v6, v15
	v_mov_b32_e32 v7, v11
	v_pk_add_f32 v[44:45], v[4:5], v[6:7]
	v_mov_b32_e32 v52, v114
	v_mov_b32_e32 v53, v115
	v_mov_b32_e32 v54, v116
	v_mov_b32_e32 v55, v117
	global_load_dwordx4 v[0:3], v[24:25], off
	global_load_dwordx4 v[4:7], v[18:19], off
	v_mov_b32_e32 v57, v40
	v_mov_b32_e32 v59, v41
	v_mov_b32_e32 v56, v52
	v_mov_b32_e32 v58, v53
	v_pk_add_f32 v[56:57], v[56:57], v[58:59]
	v_mov_b32_e32 v58, v54
	v_mov_b32_e32 v59, v42
	v_pk_add_f32 v[56:57], v[56:57], v[58:59]
	v_mov_b32_e32 v58, v55
	v_mov_b32_e32 v59, v43
	v_pk_add_f32 v[56:57], v[56:57], v[58:59]
	s_nop 0
	v_add_f32_e32 v17, 0, v56
	v_add_f32_e32 v17, v17, v57
	v_add_f32_e32 v17, v17, v44
	v_add_f32_e32 v17, v17, v45
	ds_bpermute_b32 v21, v46, v17
	s_waitcnt lgkmcnt(0)
	v_add_f32_e32 v17, v17, v21
	ds_bpermute_b32 v21, v47, v17
	s_waitcnt lgkmcnt(0)
	v_add_f32_e32 v17, v17, v21
	ds_bpermute_b32 v21, v49, v17
	s_waitcnt lgkmcnt(0)
	v_add_f32_e32 v17, v17, v21
	ds_bpermute_b32 v21, v50, v17
	s_waitcnt lgkmcnt(0)
	v_add_f32_e32 v17, v17, v21
	ds_bpermute_b32 v21, v51, v17
	s_waitcnt lgkmcnt(0)
	v_add_f32_e32 v17, v17, v21
	ds_bpermute_b32 v21, v48, v17
	s_waitcnt lgkmcnt(0)
	v_add_f32_e32 v17, v17, v21
	v_mul_f32_e32 v44, 0x3a800000, v17
	v_pk_add_f32 v[52:53], v[52:53], v[44:45] op_sel_hi:[1,0] neg_lo:[0,1] neg_hi:[0,1]
	v_pk_add_f32 v[40:41], v[40:41], v[44:45] op_sel_hi:[1,0] neg_lo:[0,1] neg_hi:[0,1]
	v_mov_b32_e32 v58, v53
	v_mov_b32_e32 v59, v41
	v_pk_add_f32 v[54:55], v[54:55], v[44:45] op_sel_hi:[1,0] neg_lo:[0,1] neg_hi:[0,1]
	v_pk_add_f32 v[42:43], v[42:43], v[44:45] op_sel_hi:[1,0] neg_lo:[0,1] neg_hi:[0,1]
	v_mov_b32_e32 v56, v52
	v_mov_b32_e32 v57, v40
	v_pk_mul_f32 v[58:59], v[58:59], v[58:59]
	v_pk_add_f32 v[12:13], v[12:13], v[44:45] op_sel_hi:[1,0] neg_lo:[0,1] neg_hi:[0,1]
	v_pk_fma_f32 v[56:57], v[56:57], v[56:57], v[58:59]
	v_mov_b32_e32 v58, v54
	v_mov_b32_e32 v59, v42
	v_pk_fma_f32 v[56:57], v[58:59], v[58:59], v[56:57]
	v_mov_b32_e32 v58, v55
	v_mov_b32_e32 v59, v43
	v_pk_add_f32 v[8:9], v[8:9], v[44:45] op_sel_hi:[1,0] neg_lo:[0,1] neg_hi:[0,1]
	v_pk_fma_f32 v[56:57], v[58:59], v[58:59], v[56:57]
	v_mov_b32_e32 v58, v9
	v_mov_b32_e32 v59, v13
	v_pk_add_f32 v[14:15], v[14:15], v[44:45] op_sel_hi:[1,0] neg_lo:[0,1] neg_hi:[0,1]
	v_pk_add_f32 v[10:11], v[10:11], v[44:45] op_sel_hi:[1,0] neg_lo:[0,1] neg_hi:[0,1]
	v_mov_b32_e32 v44, v8
	v_mov_b32_e32 v45, v12
	v_pk_mul_f32 v[58:59], v[58:59], v[58:59]
	v_add_f32_e32 v17, v56, v57
	v_pk_fma_f32 v[44:45], v[44:45], v[44:45], v[58:59]
	v_mov_b32_e32 v58, v10
	v_mov_b32_e32 v59, v14
	v_pk_fma_f32 v[44:45], v[58:59], v[58:59], v[44:45]
	v_mov_b32_e32 v58, v11
	v_mov_b32_e32 v59, v15
	v_pk_fma_f32 v[44:45], v[58:59], v[58:59], v[44:45]
	s_nop 0
	v_add_f32_e32 v17, v45, v17
	v_add_f32_e32 v17, v44, v17
	ds_bpermute_b32 v21, v46, v17
	s_waitcnt lgkmcnt(0)
	v_add_f32_e32 v17, v17, v21
	ds_bpermute_b32 v21, v47, v17
	s_waitcnt lgkmcnt(0)
	v_add_f32_e32 v17, v17, v21
	ds_bpermute_b32 v21, v49, v17
	s_waitcnt lgkmcnt(0)
	v_add_f32_e32 v17, v17, v21
	ds_bpermute_b32 v21, v50, v17
	s_waitcnt lgkmcnt(0)
	v_add_f32_e32 v17, v17, v21
	ds_bpermute_b32 v21, v51, v17
	s_waitcnt lgkmcnt(0)
	v_add_f32_e32 v17, v17, v21
	ds_bpermute_b32 v21, v48, v17
	s_waitcnt lgkmcnt(0)
	v_add_f32_e32 v17, v17, v21
	v_fmamk_f32 v17, v17, 0x3a800000, v181
	v_cmp_gt_f32_e32 vcc, s10, v17
	v_mul_f32_e32 v21, 0x4b800000, v17
	s_nop 0
	v_cndmask_b32_e32 v17, v17, v21, vcc
	v_rsq_f32_e32 v17, v17
	s_nop 0
	v_mul_f32_e32 v21, 0x45800000, v17
	v_cndmask_b32_e32 v44, v17, v21, vcc
	v_pk_mul_f32 v[52:53], v[52:53], v[44:45] op_sel_hi:[1,0]
	s_and_b64 vcc, exec, s[0:1]
	s_waitcnt vmcnt(0)
	v_pk_fma_f32 v[0:1], v[0:1], v[52:53], v[4:5]
	v_pk_mul_f32 v[4:5], v[54:55], v[44:45] op_sel_hi:[1,0]
	s_nop 0
	v_pk_fma_f32 v[2:3], v[2:3], v[4:5], v[6:7]
	global_store_dwordx4 v[34:35], v[0:3], off
	s_cbranch_vccnz .LBB0_954
	v_lshl_add_u64 v[4:5], v[38:39], 0, v[96:97]
	global_load_dwordx4 v[4:7], v[4:5], off
	v_lshl_add_u64 v[52:53], v[36:37], 0, v[96:97]
	global_load_dwordx4 v[52:55], v[52:53], off
	v_mov_b32_e32 v17, v97
	s_waitcnt vmcnt(1)
	v_add_f32_e32 v4, 1.0, v4
	v_add_f32_e32 v5, 1.0, v5
	v_add_f32_e32 v6, 1.0, v6
	v_add_f32_e32 v7, 1.0, v7
	s_waitcnt vmcnt(0)
	v_fma_f32 v0, v0, v4, v52
	v_fma_f32 v1, v1, v5, v53
	v_fma_f32 v2, v2, v6, v54
	v_fmac_f32_e32 v55, v3, v7
	v_cvt_pk_bf16_f32 v0, v0, v1
	v_cvt_pk_bf16_f32 v1, v2, v55
	v_lshl_add_u64 v[2:3], v[32:33], 0, v[16:17]
	global_store_dwordx2 v[2:3], v[0:1], off

.LBB0_960:
	v_ashrrev_i32_e32 v23, 31, v22
	v_lshlrev_b64 v[0:1], 12, v[22:23]
	v_lshl_add_u64 v[0:1], s[58:59], 0, v[0:1]
	v_lshl_add_u64 v[32:33], v[0:1], 0, v[96:97]
	v_mov_b32_e32 v8, v142
	v_mov_b32_e32 v9, v143
	v_mov_b32_e32 v10, v144
	v_mov_b32_e32 v11, v145
	v_mov_b32_e32 v12, v138
	v_mov_b32_e32 v13, v139
	v_mov_b32_e32 v14, v140
	v_mov_b32_e32 v15, v141
	v_mov_b32_e32 v36, v134
	v_mov_b32_e32 v37, v135
	v_mov_b32_e32 v38, v136
	v_mov_b32_e32 v39, v137
	v_ashrrev_i32_e32 v21, 31, v20
	s_mov_b64 s[10:11], 0x1000
	v_mov_b32_e32 v1, v8
	v_mov_b32_e32 v0, v12
	v_mov_b32_e32 v2, v13
	v_mov_b32_e32 v3, v9
	v_pk_add_f32 v[0:1], v[0:1], v[2:3]
	v_mov_b32_e32 v2, v14
	v_mov_b32_e32 v3, v10
	v_pk_add_f32 v[0:1], v[0:1], v[2:3]
	v_mov_b32_e32 v2, v15
	v_mov_b32_e32 v3, v11
	v_pk_add_f32 v[44:45], v[0:1], v[2:3]
	v_ashrrev_i32_e32 v0, 12, v22
	v_add_u32_e32 v0, s38, v0
	v_mul_hi_i32_i24_e32 v1, 0x3000, v0
	v_mul_i32_i24_e32 v0, 0x3000, v0
	v_lshl_add_u64 v[22:23], s[16:17], 0, v[0:1]
	v_lshlrev_b64 v[0:1], 11, v[20:21]
	v_lshl_add_u64 v[20:21], s[80:81], 0, v[0:1]
	v_mov_b32_e32 v40, v130
	v_mov_b32_e32 v41, v131
	v_mov_b32_e32 v42, v132
	v_mov_b32_e32 v43, v133
	global_load_dwordx4 v[0:3], v[24:25], off
	global_load_dwordx4 v[4:7], v[18:19], off
	v_mov_b32_e32 v53, v36
	v_mov_b32_e32 v55, v37
	v_lshl_add_u64 v[34:35], v[22:23], 0, s[10:11]
	s_mov_b32 s10, 0x800000
	v_mov_b32_e32 v52, v40
	v_mov_b32_e32 v54, v41
	v_pk_add_f32 v[52:53], v[52:53], v[54:55]
	v_mov_b32_e32 v54, v42
	v_mov_b32_e32 v55, v38
	v_pk_add_f32 v[52:53], v[52:53], v[54:55]
	v_mov_b32_e32 v54, v43
	v_mov_b32_e32 v55, v39
	v_pk_add_f32 v[52:53], v[52:53], v[54:55]
	s_nop 0
	v_add_f32_e32 v17, 0, v52
	v_add_f32_e32 v17, v17, v53
	v_add_f32_e32 v17, v17, v44
	v_add_f32_e32 v17, v17, v45
	ds_bpermute_b32 v27, v46, v17
	s_waitcnt lgkmcnt(0)
	v_add_f32_e32 v17, v17, v27
	ds_bpermute_b32 v27, v47, v17
	s_waitcnt lgkmcnt(0)
	v_add_f32_e32 v17, v17, v27
	ds_bpermute_b32 v27, v49, v17
	s_waitcnt lgkmcnt(0)
	v_add_f32_e32 v17, v17, v27
	ds_bpermute_b32 v27, v50, v17
	s_waitcnt lgkmcnt(0)
	v_add_f32_e32 v17, v17, v27
	ds_bpermute_b32 v27, v51, v17
	s_waitcnt lgkmcnt(0)
	v_add_f32_e32 v17, v17, v27
	ds_bpermute_b32 v27, v48, v17
	s_waitcnt lgkmcnt(0)
	v_add_f32_e32 v17, v17, v27
	v_mul_f32_e32 v44, 0x3a800000, v17
	v_pk_add_f32 v[52:53], v[40:41], v[44:45] op_sel_hi:[1,0] neg_lo:[0,1] neg_hi:[0,1]
	v_pk_add_f32 v[36:37], v[36:37], v[44:45] op_sel_hi:[1,0] neg_lo:[0,1] neg_hi:[0,1]
	v_mov_b32_e32 v54, v53
	v_mov_b32_e32 v55, v37
	v_pk_add_f32 v[42:43], v[42:43], v[44:45] op_sel_hi:[1,0] neg_lo:[0,1] neg_hi:[0,1]
	v_pk_add_f32 v[38:39], v[38:39], v[44:45] op_sel_hi:[1,0] neg_lo:[0,1] neg_hi:[0,1]
	v_mov_b32_e32 v40, v52
	v_mov_b32_e32 v41, v36
	v_pk_mul_f32 v[54:55], v[54:55], v[54:55]
	v_pk_add_f32 v[12:13], v[12:13], v[44:45] op_sel_hi:[1,0] neg_lo:[0,1] neg_hi:[0,1]
	v_pk_fma_f32 v[40:41], v[40:41], v[40:41], v[54:55]
	v_mov_b32_e32 v54, v42
	v_mov_b32_e32 v55, v38
	v_pk_fma_f32 v[40:41], v[54:55], v[54:55], v[40:41]
	v_mov_b32_e32 v54, v43
	v_mov_b32_e32 v55, v39
	v_pk_add_f32 v[8:9], v[8:9], v[44:45] op_sel_hi:[1,0] neg_lo:[0,1] neg_hi:[0,1]
	v_pk_fma_f32 v[40:41], v[54:55], v[54:55], v[40:41]
	v_mov_b32_e32 v54, v9
	v_mov_b32_e32 v55, v13
	v_pk_add_f32 v[14:15], v[14:15], v[44:45] op_sel_hi:[1,0] neg_lo:[0,1] neg_hi:[0,1]
	v_pk_add_f32 v[10:11], v[10:11], v[44:45] op_sel_hi:[1,0] neg_lo:[0,1] neg_hi:[0,1]
	v_mov_b32_e32 v44, v8
	v_mov_b32_e32 v45, v12
	v_pk_mul_f32 v[54:55], v[54:55], v[54:55]
	v_add_f32_e32 v17, v40, v41
	v_pk_fma_f32 v[44:45], v[44:45], v[44:45], v[54:55]
	v_mov_b32_e32 v54, v10
	v_mov_b32_e32 v55, v14
	v_pk_fma_f32 v[44:45], v[54:55], v[54:55], v[44:45]
	v_mov_b32_e32 v54, v11
	v_mov_b32_e32 v55, v15
	v_pk_fma_f32 v[44:45], v[54:55], v[54:55], v[44:45]
	s_nop 0
	v_add_f32_e32 v17, v45, v17
	v_add_f32_e32 v17, v44, v17
	ds_bpermute_b32 v27, v46, v17
	s_waitcnt lgkmcnt(0)
	v_add_f32_e32 v17, v17, v27
	ds_bpermute_b32 v27, v47, v17
	s_waitcnt lgkmcnt(0)
	v_add_f32_e32 v17, v17, v27
	ds_bpermute_b32 v27, v49, v17
	s_waitcnt lgkmcnt(0)
	v_add_f32_e32 v17, v17, v27
	ds_bpermute_b32 v27, v50, v17
	s_waitcnt lgkmcnt(0)
	v_add_f32_e32 v17, v17, v27
	ds_bpermute_b32 v27, v51, v17
	s_waitcnt lgkmcnt(0)
	v_add_f32_e32 v17, v17, v27
	ds_bpermute_b32 v27, v48, v17
	s_waitcnt lgkmcnt(0)
	v_add_f32_e32 v17, v17, v27
	v_fmamk_f32 v17, v17, 0x3a800000, v181
	v_cmp_gt_f32_e32 vcc, s10, v17
	v_mul_f32_e32 v27, 0x4b800000, v17
	s_nop 0
	v_cndmask_b32_e32 v17, v17, v27, vcc
	v_rsq_f32_e32 v17, v17
	s_nop 0
	v_mul_f32_e32 v27, 0x45800000, v17
	v_cndmask_b32_e32 v40, v17, v27, vcc
	v_pk_mul_f32 v[44:45], v[52:53], v[40:41] op_sel_hi:[1,0]
	s_and_b64 vcc, exec, s[0:1]
	s_waitcnt vmcnt(0)
	v_pk_fma_f32 v[0:1], v[0:1], v[44:45], v[4:5]
	v_pk_mul_f32 v[4:5], v[42:43], v[40:41] op_sel_hi:[1,0]
	s_nop 0
	v_pk_fma_f32 v[2:3], v[2:3], v[4:5], v[6:7]
	global_store_dwordx4 v[32:33], v[0:3], off
	s_cbranch_vccnz .LBB0_962
	v_lshl_add_u64 v[4:5], v[34:35], 0, v[96:97]
	global_load_dwordx4 v[4:7], v[4:5], off
	v_lshl_add_u64 v[42:43], v[22:23], 0, v[96:97]
	global_load_dwordx4 v[42:45], v[42:43], off
	v_mov_b32_e32 v17, v97
	s_waitcnt vmcnt(1)
	v_add_f32_e32 v4, 1.0, v4
	v_add_f32_e32 v5, 1.0, v5
	v_add_f32_e32 v6, 1.0, v6
	v_add_f32_e32 v7, 1.0, v7
	s_waitcnt vmcnt(0)
	v_fma_f32 v0, v0, v4, v42
	v_fma_f32 v1, v1, v5, v43
	v_fma_f32 v2, v2, v6, v44
	v_fmac_f32_e32 v45, v3, v7
	v_cvt_pk_bf16_f32 v0, v0, v1
	v_cvt_pk_bf16_f32 v1, v2, v45
	v_lshl_add_u64 v[2:3], v[20:21], 0, v[16:17]
	global_store_dwordx2 v[2:3], v[0:1], off
